# P4/P6 small path: residual rows prefetched before the K-split loop; prologue weight conversion moved onto the 2 fold waves; on top of v33
# baseline (speedup 1.0000x reference)
; #define LAS __attribute__((address_space(3)))
; __device__ __forceinline__ void convert_weights(const Params& p, LAS unsigned char* lds, int first, int last, int worker, int nworkers) {
;     int tid = threadIdx.x; asm volatile("" : "+v"(tid));
;     const int lane = tid & 63, wid = __builtin_amdgcn_readfirstlane(tid >> 6);
;     LAS float* scr = (LAS float*)(lds + wid * 16384);
; #pragma unroll 1
;     for (int it = first + worker; it < last; it += nworkers) {
;         const int l = it / WI_L; int r = it % WI_L;
;         unsigned char* wb = p.ws + WS_W + (size_t)l * W_LAYER;
;         if (r < WI_IN) { const int kb = r / 52, nb = r % 52; transpose_item(p.w_in + (size_t)l * DM * INW, INW, p.norm_mix + l * DM, (bf16_t*)(wb + WO_IN), DM, nb * 64, kb * 32, nb * 64, scr, lane); continue; } r -= WI_IN;
.LBB0_51:
	v_readlane_b32 s52, v249, 4
	v_readlane_b32 s64, v249, 16
	v_readlane_b32 s65, v249, 17
	s_cmp_lg_u64 s[64:65], 0
	s_cselect_b64 s[28:29], -1, 0
	v_mov_b32_e32 v0, v222
	v_cndmask_b32_e64 v1, 0, 1, s[28:29]
	s_cmpk_gt_i32 s0, 0x67f
	v_readfirstlane_b32 s4, v0
	v_cmp_ne_u32_e64 s[30:31], 1, v1
	v_readlane_b32 s53, v249, 5
	v_readlane_b32 s54, v249, 6
	v_readlane_b32 s55, v249, 7
	v_readlane_b32 s56, v249, 8
	v_readlane_b32 s57, v249, 9
	v_readlane_b32 s58, v249, 10
	v_readlane_b32 s59, v249, 11
	v_readlane_b32 s60, v249, 12
	v_readlane_b32 s61, v249, 13
	v_readlane_b32 s62, v249, 14
	v_readlane_b32 s63, v249, 15
	v_readlane_b32 s66, v249, 18
	v_readlane_b32 s67, v249, 19
	s_lshr_b32 s32, s4, 6
	s_sub_i32 s32, s32, 6
	s_mul_i32 s33, s81, 2
	s_add_i32 s33, s33, s32
	s_cmp_lt_i32 s32, 0
	s_cbranch_scc1 .LBB0_65
	s_mul_i32 s32, s92, 2
	s_cmpk_gt_i32 s33, 0x67f
	s_cbranch_scc1 .LBB0_65
	s_add_u32 s1, s50, 0x100000
	s_addc_u32 s12, s51, 0
	s_lshl_b32 s4, s4, 8
	v_lshlrev_b32_e32 v4, 3, v0
	s_and_b32 s4, s4, 0xffffc000
	v_and_b32_e32 v4, 24, v4
	s_add_i32 s4, s4, 0
	v_bfe_u32 v32, v0, 4, 2
	v_lshlrev_b32_e32 v1, 2, v0
	v_bfe_u32 v43, v0, 2, 4
	v_mul_u32_u24_e32 v5, 0x104, v4
	v_and_b32_e32 v0, 60, v0
	v_and_b32_e32 v2, 60, v1
	v_add3_u32 v44, s4, v5, v0
	v_or_b32_e32 v0, 4, v32
	v_mov_b32_e32 v35, 0
	v_lshl_add_u32 v1, v2, 2, s4
	v_mul_u32_u24_e32 v3, 0x104, v32
	v_mul_u32_u24_e32 v0, 0x104, v0
	v_or_b32_e32 v45, 16, v43
	v_or_b32_e32 v46, 32, v43
	v_or_b32_e32 v47, 48, v43
	v_mov_b32_e32 v33, v35
	v_lshlrev_b32_e32 v36, 2, v2
	v_mov_b32_e32 v37, v35
	s_mov_b32 s13, 0xd000
	s_mov_b32 s14, 0x1a000
	s_mov_b32 s15, 0x27000
	s_mov_b32 s16, 0x34000
	v_add_u32_e32 v48, v1, v3
	v_lshlrev_b32_e32 v34, 1, v4
	v_add_u32_e32 v49, v1, v0
	s_mov_b32 s17, s33
	s_branch .LBB0_55

; #define LAS __attribute__((address_space(3)))
; __device__ __forceinline__ unsigned cvt_pk_bf16(float lo, float hi) { unsigned r; asm volatile("v_cvt_pk_bf16_f32 %0, %1, %2" : "=v"(r) : "v"(lo), "v"(hi)); return r; }
; __device__ __forceinline__ void transpose_item(const float* W, int N, const float* ks, bf16_t* WT, int ldo, int orow0, int k0, int n0, LAS float* scr, int lane) {
;     ...
;     for (int i = 0; i < 8; ++i) { const int kk = i * 4 + (lane >> 4); const float sc = ks ? ks[k0 + kk] : 1.0f; LAS float* d = scr + kk * 65 + 4 * (lane & 15);
;         d[0] = v[i][0] * sc; d[1] = v[i][1] * sc; d[2] = v[i][2] * sc; d[3] = v[i][3] * sc; }
;     asm volatile("s_waitcnt lgkmcnt(0)" ::: "memory");
;     const int kc = lane & 3;
; #pragma unroll
;     for (int j = 0; j < 4; ++j) { const int n = (lane >> 2) + 16 * j; const LAS float* s = scr + (8 * kc) * 65 + n;
;         u32x4 o; o.x = cvt_pk_bf16(s[0 * 65], s[1 * 65]); o.y = cvt_pk_bf16(s[2 * 65], s[3 * 65]); o.z = cvt_pk_bf16(s[4 * 65], s[5 * 65]); o.w = cvt_pk_bf16(s[6 * 65], s[7 * 65]);
;         *(u32x4*)(WT + (size_t)(orow0 + n) * ldo + k0 + 8 * kc) = o; }
;     asm volatile("s_waitcnt lgkmcnt(0)" ::: "memory");
; }
; __device__ __forceinline__ void convert_weights(const Params& p, LAS unsigned char* lds, int first, int last, int worker, int nworkers) {
;     int tid = threadIdx.x; asm volatile("" : "+v"(tid));
;     const int lane = tid & 63, wid = __builtin_amdgcn_readfirstlane(tid >> 6);
;     LAS float* scr = (LAS float*)(lds + wid * 16384);
; #pragma unroll 1
;     for (int it = first + worker; it < last; it += nworkers) {
.LBB0_54:
	v_add_u32_e32 v9, 0x1450, v49
	ds_write2_b32 v9, v4, v5 offset1:1
	v_add_u32_e32 v4, 0x1458, v49
	ds_write2_b32 v4, v6, v7 offset1:1
	s_waitcnt vmcnt(0)
	v_pk_mul_f32 v[0:1], v[0:1], v[8:9] op_sel_hi:[1,0]
	v_add_u32_e32 v4, 0x1860, v49
	ds_write2_b32 v4, v0, v1 offset1:1
	v_pk_mul_f32 v[0:1], v[2:3], v[8:9] op_sel_hi:[1,0]
	v_add_u32_e32 v2, 0x1868, v49
	ds_write2_b32 v2, v0, v1 offset1:1
	s_waitcnt lgkmcnt(0)
	ds_read2_b32 v[0:1], v44 offset1:65
	s_waitcnt lgkmcnt(0)
	v_cvt_pk_bf16_f32 v0, v0, v1
	ds_read2_b32 v[2:3], v44 offset0:130 offset1:195
	v_add_u32_e32 v10, 0x400, v44
	s_mul_hi_i32 s5, s18, 0x1b00000
	s_mul_i32 s18, s18, 0x1b00000
	s_waitcnt lgkmcnt(0)
	v_cvt_pk_bf16_f32 v1, v2, v3
	ds_read2_b32 v[2:3], v10 offset0:4 offset1:69
	s_add_u32 s10, s1, s18
	s_addc_u32 s5, s12, s5
	s_waitcnt lgkmcnt(0)
	v_cvt_pk_bf16_f32 v2, v2, v3
	ds_read2_b32 v[4:5], v10 offset0:134 offset1:199
	s_lshl_b64 s[8:9], s[8:9], 1
	s_add_u32 s8, s10, s8
	s_waitcnt lgkmcnt(0)
	v_cvt_pk_bf16_f32 v3, v4, v5
	v_or_b32_e32 v4, s4, v43
	s_addc_u32 s9, s5, s9
	v_ashrrev_i32_e32 v5, 31, v4
	v_lshl_add_u64 v[6:7], s[8:9], 0, v[34:35]
	v_lshlrev_b64 v[4:5], 11, v[4:5]
	ds_read2_b32 v[8:9], v44 offset0:16 offset1:81
	v_lshl_add_u64 v[4:5], v[6:7], 0, v[4:5]
	global_store_dwordx4 v[4:5], v[0:3], off
	s_add_i32 s17, s17, s32
	s_cmpk_lt_i32 s17, 0x680
	s_waitcnt lgkmcnt(0)
	v_cvt_pk_bf16_f32 v0, v8, v9
	v_or_b32_e32 v8, s4, v45
	ds_read2_b32 v[2:3], v44 offset0:146 offset1:211
	v_ashrrev_i32_e32 v9, 31, v8
	s_waitcnt lgkmcnt(0)
	v_cvt_pk_bf16_f32 v1, v2, v3
	ds_read2_b32 v[2:3], v10 offset0:20 offset1:85
	v_lshlrev_b64 v[8:9], 11, v[8:9]
	s_waitcnt lgkmcnt(0)
	v_cvt_pk_bf16_f32 v2, v2, v3
	ds_read2_b32 v[4:5], v10 offset0:150 offset1:215
	s_waitcnt lgkmcnt(0)
	v_cvt_pk_bf16_f32 v3, v4, v5
	v_lshl_add_u64 v[8:9], v[6:7], 0, v[8:9]
	ds_read2_b32 v[4:5], v44 offset0:32 offset1:97
	global_store_dwordx4 v[8:9], v[0:3], off
	v_or_b32_e32 v8, s4, v46
	v_ashrrev_i32_e32 v9, 31, v8
	s_waitcnt lgkmcnt(0)
	v_cvt_pk_bf16_f32 v0, v4, v5
	ds_read2_b32 v[2:3], v44 offset0:162 offset1:227
	s_waitcnt lgkmcnt(0)
	v_cvt_pk_bf16_f32 v1, v2, v3
	ds_read2_b32 v[2:3], v10 offset0:36 offset1:101
	s_waitcnt lgkmcnt(0)
	v_cvt_pk_bf16_f32 v2, v2, v3
	ds_read2_b32 v[4:5], v10 offset0:166 offset1:231
	v_lshlrev_b64 v[8:9], 11, v[8:9]
	s_waitcnt lgkmcnt(0)
	v_cvt_pk_bf16_f32 v3, v4, v5
	ds_read2_b32 v[4:5], v44 offset0:48 offset1:113
	v_lshl_add_u64 v[8:9], v[6:7], 0, v[8:9]
	global_store_dwordx4 v[8:9], v[0:3], off
	s_waitcnt lgkmcnt(0)
	s_nop 0
	v_cvt_pk_bf16_f32 v0, v4, v5
	v_or_b32_e32 v4, s4, v47
	v_ashrrev_i32_e32 v5, 31, v4
	ds_read2_b32 v[2:3], v44 offset0:178 offset1:243
	v_lshlrev_b64 v[4:5], 11, v[4:5]
	s_waitcnt lgkmcnt(0)
	v_cvt_pk_bf16_f32 v1, v2, v3
	ds_read2_b32 v[2:3], v10 offset0:52 offset1:117
	v_lshl_add_u64 v[4:5], v[6:7], 0, v[4:5]
	s_waitcnt lgkmcnt(0)
	v_cvt_pk_bf16_f32 v2, v2, v3
	ds_read2_b32 v[8:9], v10 offset0:182 offset1:247
	s_waitcnt lgkmcnt(0)
	v_cvt_pk_bf16_f32 v3, v8, v9
	global_store_dwordx4 v[4:5], v[0:3], off
	s_waitcnt lgkmcnt(0)
	s_cbranch_scc0 .LBB0_65

; #define LAS __attribute__((address_space(3)))
; template <int KSTEPS  >
; __device__ __forceinline__ void small_mma_ksplit(f32x4 (&acc)[2], const bf16_t* A, int lda, const bf16_t* Bt, int ldb, int n0, LAS unsigned char* lds, const SmallId& id) {
;     ...
;     for (int ks = 0; ks < KSTEPS; ++ks) {
;         bf16x8 a[8], b[2];
; #pragma unroll
;         for (int rb = 0; rb < 8; ++rb) a[rb] = *(const bf16x8*)(ap + (size_t)(16 * rb) * lda + 32 * ks);
;         b[0] = *(const bf16x8*)(bp + 32 * ks); b[1] = *(const bf16x8*)(bp + (size_t)16 * ldb + 32 * ks);
; #pragma unroll
;         for (int rb = 0; rb < 8; ++rb) { part[rb][0] = __builtin_amdgcn_mfma_f32_16x16x32_bf16(b[0], a[rb], part[rb][0], 0, 0, 0); part[rb][1] = __builtin_amdgcn_mfma_f32_16x16x32_bf16(b[1], a[rb], part[rb][1], 0, 0, 0); }
;     }
;     LAS f32x4* red = (LAS f32x4*)lds;
; #pragma unroll
;     for (int rb = 0; rb < 8; ++rb) { red[((id.w * 8 + rb) * 2 + 0) * 64 + lane] = part[rb][0]; red[((id.w * 8 + rb) * 2 + 1) * 64 + lane] = part[rb][1]; }
;     asm volatile("s_waitcnt lgkmcnt(0)" ::: "memory"); __syncthreads();
;     acc[0] = (f32x4){0.f, 0.f, 0.f, 0.f}; acc[1] = acc[0];
; #pragma unroll
;     for (int w2 = 0; w2 < 8; ++w2) { acc[0] += red[((w2 * 8 + id.w) * 2 + 0) * 64 + lane]; acc[1] += red[((w2 * 8 + id.w) * 2 + 1) * 64 + lane]; }
;     asm volatile("s_waitcnt lgkmcnt(0)" ::: "memory"); __syncthreads();
; template <bool RES_F32, bool OUT_F32, int KSTEPS>
; __device__ __forceinline__ void small_res(const Params& p, LAS unsigned char* lds, const bf16_t* A, int lda, const bf16_t* Bt, int K, float* ssq_next, int G, int bx) {
;     ...
;         float s = 0.f;
; #pragma unroll
;         for (int nb = 0; nb < 2; ++nb) { const int col = n0 + 16 * nb + 4 * id.fq;
;             f32x4 r;
;             if (RES_F32) r = *(const f32x4*)(p.xs + (size_t)(id.row - MP) * DM + col);
;             else { const u32x2 w = *(const u32x2*)(XB + (size_t)id.row * DM + col); r = (f32x4){bf_lo(w.x), bf_hi(w.x), bf_lo(w.y), bf_hi(w.y)}; }
;             const f32x4 x = r + acc[nb];
;             if (OUT_F32) *(f32x4*)(p.out + (size_t)id.row * DM + col) = x;
;             else { u32x2 w; w.x = cvt_pk_bf16(x[0], x[1]); w.y = cvt_pk_bf16(x[2], x[3]); *(u32x2*)(XB + (size_t)id.row * DM + col) = w; }
;             s += (x[0] * x[0] + x[1] * x[1]) + (x[2] * x[2] + x[3] * x[3]); }
.LBB0_863:
	v_lshl_or_b32 v218, s7, 5, v86
	v_ashrrev_i32_e32 v219, 31, v218
	v_lshl_add_u64 v[220:221], v[218:219], 1, v[64:65]
	global_load_dwordx2 v[250:251], v[220:221], off
	global_load_dwordx2 v[234:235], v[220:221], off offset:32
	s_waitcnt lgkmcnt(0)
	v_readlane_b32 s8, v246, 8
	v_readfirstlane_b32 s32, v222
	s_bfe_u32 s8, s8, 0x30003
	s_lshr_b32 s32, s32, 6
	s_cmp_eq_u32 s32, s8
	s_cselect_b32 s32, 1, 0
	s_lshl_b32 s9, s8, 11
	v_add_u32_e32 v68, s9, v76
	s_sub_i32 s9, s11, s10
	s_mul_i32 s8, s8, s9
	s_add_i32 s8, s8, s10
	s_mov_b32 s9, 0
	v_lshl_add_u64 v[70:71], v[72:73], 0, s[8:9]
	s_mov_b32 s8, s18
	v_lshl_add_u64 v[88:89], v[74:75], 0, s[8:9]
	s_mov_b32 s8, s19
	v_lshl_add_u64 v[90:91], v[74:75], 0, s[8:9]
	global_load_dwordx4 v[92:95], v[70:71], off
	global_load_dwordx4 v[98:101], v[88:89], off
	global_load_dwordx4 v[102:105], v[90:91], off
	global_load_dwordx4 v[106:109], v[70:71], off offset:64
	global_load_dwordx4 v[110:113], v[88:89], off offset:64
	global_load_dwordx4 v[114:117], v[90:91], off offset:64
	global_load_dwordx4 v[118:121], v[70:71], off offset:128
	global_load_dwordx4 v[122:125], v[88:89], off offset:128
	global_load_dwordx4 v[126:129], v[90:91], off offset:128
	global_load_dwordx4 v[130:133], v[70:71], off offset:192
	global_load_dwordx4 v[134:137], v[88:89], off offset:192
	global_load_dwordx4 v[138:141], v[90:91], off offset:192
	s_waitcnt vmcnt(9)
	v_mfma_f32_16x16x32_bf16 v[36:39], v[98:101], v[92:95], v[36:39]
	v_mfma_f32_16x16x32_bf16 v[24:27], v[102:105], v[92:95], v[24:27]
	s_waitcnt vmcnt(6)
	v_mfma_f32_16x16x32_bf16 v[36:39], v[110:113], v[106:109], v[36:39]
	v_mfma_f32_16x16x32_bf16 v[24:27], v[114:117], v[106:109], v[24:27]
	s_waitcnt vmcnt(3)
	v_mfma_f32_16x16x32_bf16 v[36:39], v[122:125], v[118:121], v[36:39]
	v_mfma_f32_16x16x32_bf16 v[24:27], v[126:129], v[118:121], v[24:27]
	s_waitcnt vmcnt(0)
	v_mfma_f32_16x16x32_bf16 v[36:39], v[134:137], v[130:133], v[36:39]
	v_mfma_f32_16x16x32_bf16 v[24:27], v[138:141], v[130:133], v[24:27]
	s_nop 7
	s_nop 1
	ds_write_b128 v68, v[36:39]
	ds_write_b128 v68, v[24:27] offset:1024
	s_waitcnt lgkmcnt(0)
	s_waitcnt lgkmcnt(0)
	s_barrier
	ds_read_b128 v[92:95], v77
	ds_read_b128 v[98:101], v77 offset:1024
	ds_read_b128 v[102:105], v77 offset:16384
	ds_read_b128 v[106:109], v77 offset:17408
	ds_read_b128 v[110:113], v77 offset:32768
	ds_read_b128 v[114:117], v77 offset:33792
	ds_read_b128 v[118:121], v77 offset:49152
	ds_read_b128 v[122:125], v77 offset:50176
	ds_read_b128 v[126:129], v78
	ds_read_b128 v[130:133], v79
	ds_read_b128 v[134:137], v80
	ds_read_b128 v[138:141], v81
	ds_read_b128 v[142:145], v82
	ds_read_b128 v[146:149], v83
	ds_read_b128 v[150:153], v84
	ds_read_b128 v[0:3], v85
	s_waitcnt lgkmcnt(0)
	v_pk_add_f32 v[4:5], v[94:95], 0 op_sel_hi:[1,0]
	v_pk_add_f32 v[6:7], v[92:93], 0 op_sel_hi:[1,0]
	v_pk_add_f32 v[8:9], v[100:101], 0 op_sel_hi:[1,0]
	v_pk_add_f32 v[10:11], v[98:99], 0 op_sel_hi:[1,0]
	v_pk_add_f32 v[4:5], v[4:5], v[104:105]
	v_pk_add_f32 v[6:7], v[6:7], v[102:103]
	v_pk_add_f32 v[8:9], v[8:9], v[108:109]
	v_pk_add_f32 v[10:11], v[10:11], v[106:107]
	v_pk_add_f32 v[4:5], v[4:5], v[112:113]
	v_pk_add_f32 v[6:7], v[6:7], v[110:111]
	v_pk_add_f32 v[8:9], v[8:9], v[116:117]
	v_pk_add_f32 v[10:11], v[10:11], v[114:115]
	v_pk_add_f32 v[4:5], v[4:5], v[120:121]
	v_pk_add_f32 v[6:7], v[6:7], v[118:119]
	v_pk_add_f32 v[8:9], v[8:9], v[124:125]
	v_pk_add_f32 v[10:11], v[10:11], v[122:123]
	v_pk_add_f32 v[4:5], v[4:5], v[128:129]
	v_pk_add_f32 v[6:7], v[6:7], v[126:127]
	v_pk_add_f32 v[8:9], v[8:9], v[132:133]
	v_pk_add_f32 v[10:11], v[10:11], v[130:131]
	v_pk_add_f32 v[4:5], v[4:5], v[136:137]
	v_pk_add_f32 v[6:7], v[6:7], v[134:135]
	v_pk_add_f32 v[8:9], v[8:9], v[140:141]
	v_pk_add_f32 v[10:11], v[10:11], v[138:139]
	v_pk_add_f32 v[4:5], v[4:5], v[144:145]
	v_pk_add_f32 v[6:7], v[6:7], v[142:143]
	v_pk_add_f32 v[8:9], v[8:9], v[148:149]
	v_pk_add_f32 v[10:11], v[10:11], v[146:147]
	v_pk_add_f32 v[4:5], v[4:5], v[152:153]
	v_pk_add_f32 v[6:7], v[6:7], v[150:151]
	s_waitcnt lgkmcnt(0)
	s_waitcnt lgkmcnt(0)
	s_barrier
	s_mul_i32 exec_lo, s32, -1
	s_mov_b32 exec_hi, exec_lo
	v_pk_add_f32 v[2:3], v[8:9], v[2:3]
	v_lshl_or_b32 v8, s7, 5, v86
	v_ashrrev_i32_e32 v9, 31, v8
	v_lshl_add_u64 v[8:9], v[8:9], 1, v[64:65]
	v_pk_add_f32 v[0:1], v[10:11], v[0:1]
	v_mov_b64_e32 v[10:11], v[250:251]
	s_waitcnt vmcnt(0) lgkmcnt(0)
	v_lshlrev_b32_e32 v12, 16, v10
	v_and_b32_e32 v13, 0xffff0000, v10
	v_lshlrev_b32_e32 v10, 16, v11
	v_and_b32_e32 v11, 0xffff0000, v11
	v_pk_add_f32 v[4:5], v[4:5], v[10:11]
	v_pk_add_f32 v[6:7], v[6:7], v[12:13]
	s_nop 0
	v_cvt_pk_bf16_f32 v10, v6, v7
	v_cvt_pk_bf16_f32 v11, v4, v5
	v_mul_f32_e32 v7, v7, v7
	v_mul_f32_e32 v5, v5, v5
	v_fmac_f32_e32 v7, v6, v6
	v_fmac_f32_e32 v5, v4, v4
	global_store_dwordx2 v[8:9], v[10:11], off
	v_add_f32_e32 v10, v7, v5
	s_waitcnt vmcnt(0) lgkmcnt(0)
	v_lshlrev_b32_e32 v6, 16, v234
	v_and_b32_e32 v7, 0xffff0000, v234
	v_lshlrev_b32_e32 v4, 16, v235
	v_and_b32_e32 v5, 0xffff0000, v235
	v_pk_add_f32 v[0:1], v[0:1], v[6:7]
	v_pk_add_f32 v[2:3], v[2:3], v[4:5]
	v_cvt_pk_bf16_f32 v4, v0, v1
	v_mul_f32_e32 v1, v1, v1
	v_fmac_f32_e32 v1, v0, v0
	v_mul_f32_e32 v0, v3, v3
	v_cvt_pk_bf16_f32 v5, v2, v3
	v_fmac_f32_e32 v0, v2, v2
	v_and_b32_e32 v2, 64, v225
	v_add_f32_e32 v0, v1, v0
	v_xor_b32_e32 v1, 16, v225
	v_add_u32_e32 v2, 64, v2
	v_cmp_lt_i32_e64 s[0:1], v1, v2
	v_add_f32_e32 v0, v10, v0
	global_store_dwordx2 v[8:9], v[4:5], off offset:32
	v_cndmask_b32_e64 v1, v225, v1, s[0:1]
	v_lshlrev_b32_e32 v1, 2, v1
	ds_bpermute_b32 v1, v1, v0
	s_waitcnt lgkmcnt(0)
	v_add_f32_e32 v0, v0, v1
	v_xor_b32_e32 v1, 32, v225
	v_cmp_lt_i32_e64 s[0:1], v1, v2
	s_nop 1
	v_cndmask_b32_e64 v1, v225, v1, s[0:1]
	v_lshlrev_b32_e32 v1, 2, v1
	ds_bpermute_b32 v1, v1, v0
	s_and_saveexec_b64 s[0:1], vcc
	s_cbranch_execz .LBB0_861
	s_waitcnt lgkmcnt(0)
	v_add_f32_e32 v0, v0, v1
	global_atomic_add_f32 v[66:67], v0, off
	s_branch .LBB0_861

; template <int KSTEPS  >
; __device__ __forceinline__ void small_mma_ksplit(f32x4 (&acc)[2], const bf16_t* A, int lda, const bf16_t* Bt, int ldb, int n0, LAS unsigned char* lds, const SmallId& id) {
;     ...
;     for (int ks = 0; ks < KSTEPS; ++ks) {
;         bf16x8 a[8], b[2];
; #pragma unroll
;         for (int rb = 0; rb < 8; ++rb) a[rb] = *(const bf16x8*)(ap + (size_t)(16 * rb) * lda + 32 * ks);
;         b[0] = *(const bf16x8*)(bp + 32 * ks); b[1] = *(const bf16x8*)(bp + (size_t)16 * ldb + 32 * ks);
; #pragma unroll
;         for (int rb = 0; rb < 8; ++rb) { part[rb][0] = __builtin_amdgcn_mfma_f32_16x16x32_bf16(b[0], a[rb], part[rb][0], 0, 0, 0); part[rb][1] = __builtin_amdgcn_mfma_f32_16x16x32_bf16(b[1], a[rb], part[rb][1], 0, 0, 0); }
;     }
;     LAS f32x4* red = (LAS f32x4*)lds;
; #pragma unroll
;     for (int rb = 0; rb < 8; ++rb) { red[((id.w * 8 + rb) * 2 + 0) * 64 + lane] = part[rb][0]; red[((id.w * 8 + rb) * 2 + 1) * 64 + lane] = part[rb][1]; }
;     asm volatile("s_waitcnt lgkmcnt(0)" ::: "memory"); __syncthreads();
;     acc[0] = (f32x4){0.f, 0.f, 0.f, 0.f}; acc[1] = acc[0];
; #pragma unroll
;     for (int w2 = 0; w2 < 8; ++w2) { acc[0] += red[((w2 * 8 + id.w) * 2 + 0) * 64 + lane]; acc[1] += red[((w2 * 8 + id.w) * 2 + 1) * 64 + lane]; }
;     asm volatile("s_waitcnt lgkmcnt(0)" ::: "memory"); __syncthreads();
; template <bool RES_F32, bool OUT_F32, int KSTEPS>
; __device__ __forceinline__ void small_res(const Params& p, LAS unsigned char* lds, const bf16_t* A, int lda, const bf16_t* Bt, int K, float* ssq_next, int G, int bx) {
;     ...
;         for (int nb = 0; nb < 2; ++nb) { const int col = n0 + 16 * nb + 4 * id.fq;
;             f32x4 r;
;             if (RES_F32) r = *(const f32x4*)(p.xs + (size_t)(id.row - MP) * DM + col);
;             else { const u32x2 w = *(const u32x2*)(XB + (size_t)id.row * DM + col); r = (f32x4){bf_lo(w.x), bf_hi(w.x), bf_lo(w.y), bf_hi(w.y)}; }
;             const f32x4 x = r + acc[nb];
;             if (OUT_F32) *(f32x4*)(p.out + (size_t)id.row * DM + col) = x;
;             else { u32x2 w; w.x = cvt_pk_bf16(x[0], x[1]); w.y = cvt_pk_bf16(x[2], x[3]); *(u32x2*)(XB + (size_t)id.row * DM + col) = w; }
;             s += (x[0] * x[0] + x[1] * x[1]) + (x[2] * x[2] + x[3] * x[3]); }
;         if (!OUT_F32) { s += __shfl_xor(s, 16); s += __shfl_xor(s, 32); if (id.fq == 0) atomicAdd(ssq_next + id.row, s); }
.LBB0_908:
	v_lshl_or_b32 v218, s7, 5, v88
	v_ashrrev_i32_e32 v219, 31, v218
	v_lshl_add_u64 v[220:221], v[218:219], 2, v[68:69]
	global_load_dwordx4 v[250:253], v[220:221], off
	global_load_dwordx4 v[234:237], v[220:221], off offset:64
	s_waitcnt lgkmcnt(0)
	v_readlane_b32 s8, v246, 8
	v_readfirstlane_b32 s32, v222
	s_bfe_u32 s8, s8, 0x30003
	s_lshr_b32 s32, s32, 6
	s_cmp_eq_u32 s32, s8
	s_cselect_b32 s32, 1, 0
	s_lshl_b32 s9, s8, 11
	v_add_u32_e32 v70, s9, v78
	s_sub_i32 s9, s11, s10
	s_mul_i32 s8, s8, s9
	s_add_i32 s8, s8, s10
	s_mov_b32 s9, 0
	v_lshl_add_u64 v[72:73], v[74:75], 0, s[8:9]
	s_mov_b32 s8, s18
	v_lshl_add_u64 v[90:91], v[76:77], 0, s[8:9]
	s_mov_b32 s8, s19
	v_lshl_add_u64 v[92:93], v[76:77], 0, s[8:9]
	global_load_dwordx4 v[98:101], v[72:73], off
	global_load_dwordx4 v[102:105], v[90:91], off
	global_load_dwordx4 v[106:109], v[92:93], off
	global_load_dwordx4 v[110:113], v[72:73], off offset:64
	global_load_dwordx4 v[114:117], v[90:91], off offset:64
	global_load_dwordx4 v[118:121], v[92:93], off offset:64
	global_load_dwordx4 v[122:125], v[72:73], off offset:128
	global_load_dwordx4 v[126:129], v[90:91], off offset:128
	global_load_dwordx4 v[130:133], v[92:93], off offset:128
	global_load_dwordx4 v[134:137], v[72:73], off offset:192
	global_load_dwordx4 v[138:141], v[90:91], off offset:192
	global_load_dwordx4 v[142:145], v[92:93], off offset:192
	s_waitcnt vmcnt(9)
	v_mfma_f32_16x16x32_bf16 v[36:39], v[102:105], v[98:101], v[36:39]
	v_mfma_f32_16x16x32_bf16 v[24:27], v[106:109], v[98:101], v[24:27]
	s_waitcnt vmcnt(6)
	v_mfma_f32_16x16x32_bf16 v[36:39], v[114:117], v[110:113], v[36:39]
	v_mfma_f32_16x16x32_bf16 v[24:27], v[118:121], v[110:113], v[24:27]
	s_waitcnt vmcnt(3)
	v_mfma_f32_16x16x32_bf16 v[36:39], v[126:129], v[122:125], v[36:39]
	v_mfma_f32_16x16x32_bf16 v[24:27], v[130:133], v[122:125], v[24:27]
	s_waitcnt vmcnt(0)
	v_mfma_f32_16x16x32_bf16 v[36:39], v[138:141], v[134:137], v[36:39]
	v_mfma_f32_16x16x32_bf16 v[24:27], v[142:145], v[134:137], v[24:27]
	s_nop 7
	s_nop 1
	ds_write_b128 v70, v[36:39]
	ds_write_b128 v70, v[24:27] offset:1024
	s_waitcnt lgkmcnt(0)
	s_waitcnt lgkmcnt(0)
	s_barrier
	ds_read_b128 v[98:101], v79
	ds_read_b128 v[102:105], v79 offset:1024
	ds_read_b128 v[106:109], v79 offset:16384
	ds_read_b128 v[110:113], v79 offset:17408
	ds_read_b128 v[114:117], v79 offset:32768
	ds_read_b128 v[118:121], v79 offset:33792
	ds_read_b128 v[122:125], v79 offset:49152
	ds_read_b128 v[126:129], v79 offset:50176
	ds_read_b128 v[130:133], v80
	ds_read_b128 v[134:137], v81
	ds_read_b128 v[138:141], v82
	ds_read_b128 v[142:145], v83
	ds_read_b128 v[146:149], v84
	ds_read_b128 v[150:153], v85
	ds_read_b128 v[154:157], v86
	ds_read_b128 v[0:3], v87
	s_waitcnt lgkmcnt(0)
	v_lshl_or_b32 v12, s7, 5, v88
	v_ashrrev_i32_e32 v13, 31, v12
	v_lshl_add_u64 v[14:15], v[12:13], 2, v[68:69]
	v_pk_add_f32 v[4:5], v[100:101], 0 op_sel_hi:[1,0]
	v_pk_add_f32 v[6:7], v[98:99], 0 op_sel_hi:[1,0]
	v_pk_add_f32 v[8:9], v[104:105], 0 op_sel_hi:[1,0]
	v_pk_add_f32 v[10:11], v[102:103], 0 op_sel_hi:[1,0]
	v_pk_add_f32 v[4:5], v[4:5], v[108:109]
	v_pk_add_f32 v[6:7], v[6:7], v[106:107]
	v_pk_add_f32 v[8:9], v[8:9], v[112:113]
	v_pk_add_f32 v[10:11], v[10:11], v[110:111]
	v_pk_add_f32 v[4:5], v[4:5], v[116:117]
	v_pk_add_f32 v[6:7], v[6:7], v[114:115]
	v_pk_add_f32 v[8:9], v[8:9], v[120:121]
	v_pk_add_f32 v[10:11], v[10:11], v[118:119]
	v_pk_add_f32 v[4:5], v[4:5], v[124:125]
	v_pk_add_f32 v[6:7], v[6:7], v[122:123]
	v_pk_add_f32 v[8:9], v[8:9], v[128:129]
	v_pk_add_f32 v[10:11], v[10:11], v[126:127]
	v_pk_add_f32 v[4:5], v[4:5], v[132:133]
	v_pk_add_f32 v[6:7], v[6:7], v[130:131]
	v_pk_add_f32 v[8:9], v[8:9], v[136:137]
	v_pk_add_f32 v[10:11], v[10:11], v[134:135]
	v_pk_add_f32 v[4:5], v[4:5], v[140:141]
	v_pk_add_f32 v[6:7], v[6:7], v[138:139]
	v_pk_add_f32 v[8:9], v[8:9], v[144:145]
	v_pk_add_f32 v[10:11], v[10:11], v[142:143]
	v_pk_add_f32 v[4:5], v[4:5], v[148:149]
	v_pk_add_f32 v[6:7], v[6:7], v[146:147]
	v_pk_add_f32 v[8:9], v[8:9], v[152:153]
	v_pk_add_f32 v[10:11], v[10:11], v[150:151]
	v_pk_add_f32 v[4:5], v[4:5], v[156:157]
	v_pk_add_f32 v[6:7], v[6:7], v[154:155]
	s_waitcnt lgkmcnt(0)
	s_waitcnt lgkmcnt(0)
	s_barrier
	s_mul_i32 exec_lo, s32, -1
	s_mov_b32 exec_hi, exec_lo
	v_pk_add_f32 v[8:9], v[8:9], v[2:3]
	v_pk_add_f32 v[10:11], v[10:11], v[0:1]
	v_mov_b64_e32 v[0:1], v[250:251]
	v_mov_b64_e32 v[2:3], v[252:253]
	s_waitcnt vmcnt(0)
	v_pk_add_f32 v[0:1], v[6:7], v[0:1]
	v_pk_add_f32 v[2:3], v[4:5], v[2:3]
	v_cvt_pk_bf16_f32 v4, v0, v1
	v_mul_f32_e32 v1, v1, v1
	v_lshl_add_u64 v[6:7], v[12:13], 1, v[64:65]
	v_fmac_f32_e32 v1, v0, v0
	v_mul_f32_e32 v0, v3, v3
	v_cvt_pk_bf16_f32 v5, v2, v3
	global_store_dwordx2 v[6:7], v[4:5], off
	v_fmac_f32_e32 v0, v2, v2
	v_add_f32_e32 v12, v1, v0
	s_waitcnt vmcnt(0)
	v_pk_add_f32 v[0:1], v[10:11], v[234:235]
	v_pk_add_f32 v[2:3], v[8:9], v[236:237]
	v_cvt_pk_bf16_f32 v4, v0, v1
	v_mul_f32_e32 v1, v1, v1
	v_fmac_f32_e32 v1, v0, v0
	v_mul_f32_e32 v0, v3, v3
	v_cvt_pk_bf16_f32 v5, v2, v3
	v_fmac_f32_e32 v0, v2, v2
	v_and_b32_e32 v2, 64, v225
	v_add_f32_e32 v0, v1, v0
	v_xor_b32_e32 v1, 16, v225
	v_add_u32_e32 v2, 64, v2
	v_cmp_lt_i32_e64 s[0:1], v1, v2
	v_add_f32_e32 v0, v12, v0
	global_store_dwordx2 v[6:7], v[4:5], off offset:32
	v_cndmask_b32_e64 v1, v225, v1, s[0:1]
	v_lshlrev_b32_e32 v1, 2, v1
	ds_bpermute_b32 v1, v1, v0
	s_waitcnt lgkmcnt(0)
	v_add_f32_e32 v0, v0, v1
	v_xor_b32_e32 v1, 32, v225
	v_cmp_lt_i32_e64 s[0:1], v1, v2
	s_nop 1
	v_cndmask_b32_e64 v1, v225, v1, s[0:1]
	v_lshlrev_b32_e32 v1, 2, v1
	ds_bpermute_b32 v1, v1, v0
	s_and_saveexec_b64 s[0:1], vcc
	s_cbranch_execz .LBB0_906
	s_waitcnt lgkmcnt(0)
	v_add_f32_e32 v0, v0, v1
	global_atomic_add_f32 v[66:67], v0, off
	s_branch .LBB0_906

; #define LAS __attribute__((address_space(3)))
; template <int KSTEPS  >
; __device__ __forceinline__ void small_mma_ksplit(f32x4 (&acc)[2], const bf16_t* A, int lda, const bf16_t* Bt, int ldb, int n0, LAS unsigned char* lds, const SmallId& id) {
;     ...
;     for (int ks = 0; ks < KSTEPS; ++ks) {
;         bf16x8 a[8], b[2];
; #pragma unroll
;         for (int rb = 0; rb < 8; ++rb) a[rb] = *(const bf16x8*)(ap + (size_t)(16 * rb) * lda + 32 * ks);
;         b[0] = *(const bf16x8*)(bp + 32 * ks); b[1] = *(const bf16x8*)(bp + (size_t)16 * ldb + 32 * ks);
; #pragma unroll
;         for (int rb = 0; rb < 8; ++rb) { part[rb][0] = __builtin_amdgcn_mfma_f32_16x16x32_bf16(b[0], a[rb], part[rb][0], 0, 0, 0); part[rb][1] = __builtin_amdgcn_mfma_f32_16x16x32_bf16(b[1], a[rb], part[rb][1], 0, 0, 0); }
;     }
;     LAS f32x4* red = (LAS f32x4*)lds;
; #pragma unroll
;     for (int rb = 0; rb < 8; ++rb) { red[((id.w * 8 + rb) * 2 + 0) * 64 + lane] = part[rb][0]; red[((id.w * 8 + rb) * 2 + 1) * 64 + lane] = part[rb][1]; }
;     asm volatile("s_waitcnt lgkmcnt(0)" ::: "memory"); __syncthreads();
; template <bool RES_F32, bool OUT_F32, int KSTEPS>
; __device__ __forceinline__ void small_res(const Params& p, LAS unsigned char* lds, const bf16_t* A, int lda, const bf16_t* Bt, int K, float* ssq_next, int G, int bx) {
;     ...
;         float s = 0.f;
; #pragma unroll
;         for (int nb = 0; nb < 2; ++nb) { const int col = n0 + 16 * nb + 4 * id.fq;
;             f32x4 r;
;             if (RES_F32) r = *(const f32x4*)(p.xs + (size_t)(id.row - MP) * DM + col);
;             else { const u32x2 w = *(const u32x2*)(XB + (size_t)id.row * DM + col); r = (f32x4){bf_lo(w.x), bf_hi(w.x), bf_lo(w.y), bf_hi(w.y)}; }
.LBB0_1223:
	v_lshl_or_b32 v218, s2, 5, v84
	v_ashrrev_i32_e32 v219, 31, v218
	v_lshl_add_u64 v[220:221], v[218:219], 1, v[64:65]
	global_load_dwordx2 v[250:251], v[220:221], off
	global_load_dwordx2 v[234:235], v[220:221], off offset:32
	s_waitcnt lgkmcnt(0)
	v_readlane_b32 s0, v246, 8
	v_readfirstlane_b32 s32, v222
	s_bfe_u32 s0, s0, 0x30003
	s_lshr_b32 s32, s32, 6
	s_cmp_eq_u32 s32, s0
	s_cselect_b32 s32, 1, 0
	s_lshl_b32 s1, s0, 11
	v_add_u32_e32 v68, s1, v74
	s_sub_i32 s1, s53, s52
	s_mul_i32 s0, s0, s1
	s_add_i32 s0, s0, s52
	s_mov_b32 s1, 0
	v_lshl_add_u64 v[86:87], v[70:71], 0, s[0:1]
	s_mov_b32 s0, s62
	v_lshl_add_u64 v[88:89], v[72:73], 0, s[0:1]
	s_mov_b32 s0, s63
	v_lshl_add_u64 v[90:91], v[72:73], 0, s[0:1]
	global_load_dwordx4 v[92:95], v[86:87], off
	global_load_dwordx4 v[98:101], v[88:89], off
	global_load_dwordx4 v[102:105], v[90:91], off
	global_load_dwordx4 v[106:109], v[86:87], off offset:64
	global_load_dwordx4 v[110:113], v[88:89], off offset:64
	global_load_dwordx4 v[114:117], v[90:91], off offset:64
	global_load_dwordx4 v[118:121], v[86:87], off offset:128
	global_load_dwordx4 v[122:125], v[88:89], off offset:128
	global_load_dwordx4 v[126:129], v[90:91], off offset:128
	global_load_dwordx4 v[130:133], v[86:87], off offset:192
	global_load_dwordx4 v[134:137], v[88:89], off offset:192
	global_load_dwordx4 v[138:141], v[90:91], off offset:192
	global_load_dwordx4 v[142:145], v[86:87], off offset:256
	global_load_dwordx4 v[146:149], v[88:89], off offset:256
	global_load_dwordx4 v[150:153], v[90:91], off offset:256
	global_load_dwordx4 v[154:157], v[86:87], off offset:320
	global_load_dwordx4 v[158:161], v[88:89], off offset:320
	global_load_dwordx4 v[162:165], v[90:91], off offset:320
	global_load_dwordx4 v[166:169], v[86:87], off offset:384
	global_load_dwordx4 v[170:173], v[88:89], off offset:384
	global_load_dwordx4 v[174:177], v[90:91], off offset:384
	global_load_dwordx4 v[178:181], v[86:87], off offset:448
	global_load_dwordx4 v[182:185], v[88:89], off offset:448
	global_load_dwordx4 v[186:189], v[90:91], off offset:448
	s_waitcnt vmcnt(21)
	v_mfma_f32_16x16x32_bf16 v[36:39], v[98:101], v[92:95], v[36:39]
	v_mfma_f32_16x16x32_bf16 v[24:27], v[102:105], v[92:95], v[24:27]
	global_load_dwordx4 v[92:95], v[86:87], off offset:512
	global_load_dwordx4 v[98:101], v[88:89], off offset:512
	global_load_dwordx4 v[102:105], v[90:91], off offset:512
	s_waitcnt vmcnt(21)
	v_mfma_f32_16x16x32_bf16 v[36:39], v[110:113], v[106:109], v[36:39]
	v_mfma_f32_16x16x32_bf16 v[24:27], v[114:117], v[106:109], v[24:27]
	global_load_dwordx4 v[106:109], v[86:87], off offset:576
	global_load_dwordx4 v[110:113], v[88:89], off offset:576
	global_load_dwordx4 v[114:117], v[90:91], off offset:576
	s_waitcnt vmcnt(21)
	v_mfma_f32_16x16x32_bf16 v[36:39], v[122:125], v[118:121], v[36:39]
	v_mfma_f32_16x16x32_bf16 v[24:27], v[126:129], v[118:121], v[24:27]
	global_load_dwordx4 v[118:121], v[86:87], off offset:640
	global_load_dwordx4 v[122:125], v[88:89], off offset:640
	global_load_dwordx4 v[126:129], v[90:91], off offset:640
	s_waitcnt vmcnt(21)
	v_mfma_f32_16x16x32_bf16 v[36:39], v[134:137], v[130:133], v[36:39]
	v_mfma_f32_16x16x32_bf16 v[24:27], v[138:141], v[130:133], v[24:27]
	s_waitcnt vmcnt(18)
	v_mfma_f32_16x16x32_bf16 v[36:39], v[146:149], v[142:145], v[36:39]
	v_mfma_f32_16x16x32_bf16 v[24:27], v[150:153], v[142:145], v[24:27]
	s_waitcnt vmcnt(15)
	v_mfma_f32_16x16x32_bf16 v[36:39], v[158:161], v[154:157], v[36:39]
	v_mfma_f32_16x16x32_bf16 v[24:27], v[162:165], v[154:157], v[24:27]
	s_waitcnt vmcnt(12)
	v_mfma_f32_16x16x32_bf16 v[36:39], v[170:173], v[166:169], v[36:39]
	v_mfma_f32_16x16x32_bf16 v[24:27], v[174:177], v[166:169], v[24:27]
	s_waitcnt vmcnt(9)
	v_mfma_f32_16x16x32_bf16 v[36:39], v[182:185], v[178:181], v[36:39]
	v_mfma_f32_16x16x32_bf16 v[24:27], v[186:189], v[178:181], v[24:27]
	s_waitcnt vmcnt(6)
	v_mfma_f32_16x16x32_bf16 v[36:39], v[98:101], v[92:95], v[36:39]
	v_mfma_f32_16x16x32_bf16 v[24:27], v[102:105], v[92:95], v[24:27]
	s_waitcnt vmcnt(3)
	v_mfma_f32_16x16x32_bf16 v[36:39], v[110:113], v[106:109], v[36:39]
	v_mfma_f32_16x16x32_bf16 v[24:27], v[114:117], v[106:109], v[24:27]
	s_waitcnt vmcnt(0)
	v_mfma_f32_16x16x32_bf16 v[36:39], v[122:125], v[118:121], v[36:39]
	v_mfma_f32_16x16x32_bf16 v[24:27], v[126:129], v[118:121], v[24:27]
	s_nop 7
	s_nop 1
	ds_write_b128 v68, v[36:39]
	ds_write_b128 v68, v[24:27] offset:1024
	s_waitcnt lgkmcnt(0)
	s_waitcnt lgkmcnt(0)
	s_barrier
; __device__ __forceinline__ unsigned cvt_pk_bf16(float lo, float hi) { unsigned r; asm volatile("v_cvt_pk_bf16_f32 %0, %1, %2" : "=v"(r) : "v"(lo), "v"(hi)); return r; }
; template <int KSTEPS  >
; __device__ __forceinline__ void small_mma_ksplit(f32x4 (&acc)[2], const bf16_t* A, int lda, const bf16_t* Bt, int ldb, int n0, LAS unsigned char* lds, const SmallId& id) {
;     ...
;     acc[0] = (f32x4){0.f, 0.f, 0.f, 0.f}; acc[1] = acc[0];
; #pragma unroll
;     for (int w2 = 0; w2 < 8; ++w2) { acc[0] += red[((w2 * 8 + id.w) * 2 + 0) * 64 + lane]; acc[1] += red[((w2 * 8 + id.w) * 2 + 1) * 64 + lane]; }
;     asm volatile("s_waitcnt lgkmcnt(0)" ::: "memory"); __syncthreads();
; template <bool RES_F32, bool OUT_F32, int KSTEPS>
; __device__ __forceinline__ void small_res(const Params& p, LAS unsigned char* lds, const bf16_t* A, int lda, const bf16_t* Bt, int K, float* ssq_next, int G, int bx) {
;     ...
;         float s = 0.f;
; #pragma unroll
;         for (int nb = 0; nb < 2; ++nb) { const int col = n0 + 16 * nb + 4 * id.fq;
;             f32x4 r;
;             if (RES_F32) r = *(const f32x4*)(p.xs + (size_t)(id.row - MP) * DM + col);
;             else { const u32x2 w = *(const u32x2*)(XB + (size_t)id.row * DM + col); r = (f32x4){bf_lo(w.x), bf_hi(w.x), bf_lo(w.y), bf_hi(w.y)}; }
;             const f32x4 x = r + acc[nb];
;             if (OUT_F32) *(f32x4*)(p.out + (size_t)id.row * DM + col) = x;
;             else { u32x2 w; w.x = cvt_pk_bf16(x[0], x[1]); w.y = cvt_pk_bf16(x[2], x[3]); *(u32x2*)(XB + (size_t)id.row * DM + col) = w; }
;             s += (x[0] * x[0] + x[1] * x[1]) + (x[2] * x[2] + x[3] * x[3]); }
	ds_read_b128 v[92:95], v75
	ds_read_b128 v[98:101], v75 offset:1024
	ds_read_b128 v[102:105], v75 offset:16384
	ds_read_b128 v[106:109], v75 offset:17408
	ds_read_b128 v[110:113], v75 offset:32768
	ds_read_b128 v[114:117], v75 offset:33792
	ds_read_b128 v[118:121], v75 offset:49152
	ds_read_b128 v[122:125], v75 offset:50176
	ds_read_b128 v[126:129], v76
	ds_read_b128 v[130:133], v77
	ds_read_b128 v[134:137], v78
	ds_read_b128 v[138:141], v79
	ds_read_b128 v[142:145], v80
	ds_read_b128 v[146:149], v81
	ds_read_b128 v[150:153], v82
	ds_read_b128 v[0:3], v83
	s_waitcnt lgkmcnt(0)
	v_lshl_or_b32 v12, s2, 5, v84
	v_ashrrev_i32_e32 v13, 31, v12
	v_lshl_add_u64 v[14:15], v[12:13], 1, v[64:65]
	s_add_i32 s2, s2, s92
	v_pk_add_f32 v[4:5], v[94:95], 0 op_sel_hi:[1,0]
	v_pk_add_f32 v[6:7], v[92:93], 0 op_sel_hi:[1,0]
	v_add_u32_e32 v85, s37, v85
	s_cmp_lt_i32 s2, 32
	v_pk_add_f32 v[8:9], v[100:101], 0 op_sel_hi:[1,0]
	v_pk_add_f32 v[10:11], v[98:99], 0 op_sel_hi:[1,0]
	v_pk_add_f32 v[4:5], v[4:5], v[104:105]
	v_pk_add_f32 v[6:7], v[6:7], v[102:103]
	v_pk_add_f32 v[8:9], v[8:9], v[108:109]
	v_pk_add_f32 v[10:11], v[10:11], v[106:107]
	v_pk_add_f32 v[4:5], v[4:5], v[112:113]
	v_pk_add_f32 v[6:7], v[6:7], v[110:111]
	v_pk_add_f32 v[8:9], v[8:9], v[116:117]
	v_pk_add_f32 v[10:11], v[10:11], v[114:115]
	v_pk_add_f32 v[4:5], v[4:5], v[120:121]
	v_pk_add_f32 v[6:7], v[6:7], v[118:119]
	v_pk_add_f32 v[8:9], v[8:9], v[124:125]
	v_pk_add_f32 v[10:11], v[10:11], v[122:123]
	v_pk_add_f32 v[4:5], v[4:5], v[128:129]
	v_pk_add_f32 v[6:7], v[6:7], v[126:127]
	v_pk_add_f32 v[8:9], v[8:9], v[132:133]
	v_pk_add_f32 v[10:11], v[10:11], v[130:131]
	v_pk_add_f32 v[4:5], v[4:5], v[136:137]
	v_pk_add_f32 v[6:7], v[6:7], v[134:135]
	v_pk_add_f32 v[8:9], v[8:9], v[140:141]
	v_pk_add_f32 v[10:11], v[10:11], v[138:139]
	v_pk_add_f32 v[4:5], v[4:5], v[144:145]
	v_pk_add_f32 v[6:7], v[6:7], v[142:143]
	v_pk_add_f32 v[8:9], v[8:9], v[148:149]
	v_pk_add_f32 v[10:11], v[10:11], v[146:147]
	v_pk_add_f32 v[4:5], v[4:5], v[152:153]
	v_pk_add_f32 v[6:7], v[6:7], v[150:151]
	s_waitcnt lgkmcnt(0)
	s_waitcnt lgkmcnt(0)
	s_barrier
	s_mul_i32 exec_lo, s32, -1
	s_mov_b32 exec_hi, exec_lo
	v_pk_add_f32 v[10:11], v[10:11], v[0:1]
	v_mov_b64_e32 v[0:1], v[250:251]
	v_pk_add_f32 v[8:9], v[8:9], v[2:3]
	s_waitcnt vmcnt(0) lgkmcnt(0)
	v_lshlrev_b32_e32 v2, 16, v0
	v_and_b32_e32 v3, 0xffff0000, v0
	v_lshlrev_b32_e32 v16, 16, v1
	v_and_b32_e32 v17, 0xffff0000, v1
	v_pk_add_f32 v[0:1], v[6:7], v[2:3]
	v_pk_add_f32 v[2:3], v[4:5], v[16:17]
	v_lshl_add_u64 v[4:5], v[12:13], 2, v[66:67]
	global_store_dwordx4 v[4:5], v[0:3], off
	s_waitcnt vmcnt(0) lgkmcnt(0)
	v_lshlrev_b32_e32 v6, 16, v234
	v_and_b32_e32 v7, 0xffff0000, v234
	v_lshlrev_b32_e32 v0, 16, v235
	v_and_b32_e32 v1, 0xffff0000, v235
	v_pk_add_f32 v[2:3], v[8:9], v[0:1]
	v_pk_add_f32 v[0:1], v[10:11], v[6:7]
	global_store_dwordx4 v[4:5], v[0:3], off offset:64
	s_cbranch_scc1 .LBB0_1222

; #define LAS __attribute__((address_space(3)))
; template <int KSTEPS  >
; __device__ __forceinline__ void small_mma_ksplit(f32x4 (&acc)[2], const bf16_t* A, int lda, const bf16_t* Bt, int ldb, int n0, LAS unsigned char* lds, const SmallId& id) {
;     ...
;     for (int ks = 0; ks < KSTEPS; ++ks) {
;         bf16x8 a[8], b[2];
; #pragma unroll
;         for (int rb = 0; rb < 8; ++rb) a[rb] = *(const bf16x8*)(ap + (size_t)(16 * rb) * lda + 32 * ks);
;         b[0] = *(const bf16x8*)(bp + 32 * ks); b[1] = *(const bf16x8*)(bp + (size_t)16 * ldb + 32 * ks);
; #pragma unroll
;         for (int rb = 0; rb < 8; ++rb) { part[rb][0] = __builtin_amdgcn_mfma_f32_16x16x32_bf16(b[0], a[rb], part[rb][0], 0, 0, 0); part[rb][1] = __builtin_amdgcn_mfma_f32_16x16x32_bf16(b[1], a[rb], part[rb][1], 0, 0, 0); }
;     }
;     LAS f32x4* red = (LAS f32x4*)lds;
; #pragma unroll
;     for (int rb = 0; rb < 8; ++rb) { red[((id.w * 8 + rb) * 2 + 0) * 64 + lane] = part[rb][0]; red[((id.w * 8 + rb) * 2 + 1) * 64 + lane] = part[rb][1]; }
;     asm volatile("s_waitcnt lgkmcnt(0)" ::: "memory"); __syncthreads();
; template <bool RES_F32, bool OUT_F32, int KSTEPS>
; __device__ __forceinline__ void small_res(const Params& p, LAS unsigned char* lds, const bf16_t* A, int lda, const bf16_t* Bt, int K, float* ssq_next, int G, int bx) {
;     ...
;         float s = 0.f;
; #pragma unroll
;         for (int nb = 0; nb < 2; ++nb) { const int col = n0 + 16 * nb + 4 * id.fq;
;             f32x4 r;
;             if (RES_F32) r = *(const f32x4*)(p.xs + (size_t)(id.row - MP) * DM + col);
;             else { const u32x2 w = *(const u32x2*)(XB + (size_t)id.row * DM + col); r = (f32x4){bf_lo(w.x), bf_hi(w.x), bf_lo(w.y), bf_hi(w.y)}; }
.LBB0_1255:
	v_lshl_or_b32 v218, s7, 5, v84
	v_ashrrev_i32_e32 v219, 31, v218
	v_lshl_add_u64 v[220:221], v[218:219], 1, v[64:65]
	global_load_dwordx2 v[250:251], v[220:221], off
	global_load_dwordx2 v[234:235], v[220:221], off offset:32
	s_waitcnt lgkmcnt(0)
	v_readlane_b32 s8, v246, 8
	v_readfirstlane_b32 s32, v222
	s_bfe_u32 s8, s8, 0x30003
	s_lshr_b32 s32, s32, 6
	s_cmp_eq_u32 s32, s8
	s_cselect_b32 s32, 1, 0
	s_lshl_b32 s9, s8, 11
	v_add_u32_e32 v68, s9, v74
	s_sub_i32 s9, s53, s52
	s_mul_i32 s8, s8, s9
	s_add_i32 s8, s8, s52
	s_mov_b32 s9, 0
	v_lshl_add_u64 v[86:87], v[70:71], 0, s[8:9]
	s_mov_b32 s8, s62
	v_lshl_add_u64 v[88:89], v[72:73], 0, s[8:9]
	s_mov_b32 s8, s63
	v_lshl_add_u64 v[90:91], v[72:73], 0, s[8:9]
	global_load_dwordx4 v[92:95], v[86:87], off
	global_load_dwordx4 v[98:101], v[88:89], off
	global_load_dwordx4 v[102:105], v[90:91], off
	global_load_dwordx4 v[106:109], v[86:87], off offset:64
	global_load_dwordx4 v[110:113], v[88:89], off offset:64
	global_load_dwordx4 v[114:117], v[90:91], off offset:64
	global_load_dwordx4 v[118:121], v[86:87], off offset:128
	global_load_dwordx4 v[122:125], v[88:89], off offset:128
	global_load_dwordx4 v[126:129], v[90:91], off offset:128
	global_load_dwordx4 v[130:133], v[86:87], off offset:192
	global_load_dwordx4 v[134:137], v[88:89], off offset:192
	global_load_dwordx4 v[138:141], v[90:91], off offset:192
	global_load_dwordx4 v[142:145], v[86:87], off offset:256
	global_load_dwordx4 v[146:149], v[88:89], off offset:256
	global_load_dwordx4 v[150:153], v[90:91], off offset:256
	global_load_dwordx4 v[154:157], v[86:87], off offset:320
	global_load_dwordx4 v[158:161], v[88:89], off offset:320
	global_load_dwordx4 v[162:165], v[90:91], off offset:320
	global_load_dwordx4 v[166:169], v[86:87], off offset:384
	global_load_dwordx4 v[170:173], v[88:89], off offset:384
	global_load_dwordx4 v[174:177], v[90:91], off offset:384
	global_load_dwordx4 v[178:181], v[86:87], off offset:448
	global_load_dwordx4 v[182:185], v[88:89], off offset:448
	global_load_dwordx4 v[186:189], v[90:91], off offset:448
	s_waitcnt vmcnt(21)
	v_mfma_f32_16x16x32_bf16 v[36:39], v[98:101], v[92:95], v[36:39]
	v_mfma_f32_16x16x32_bf16 v[24:27], v[102:105], v[92:95], v[24:27]
	global_load_dwordx4 v[92:95], v[86:87], off offset:512
	global_load_dwordx4 v[98:101], v[88:89], off offset:512
	global_load_dwordx4 v[102:105], v[90:91], off offset:512
	s_waitcnt vmcnt(21)
	v_mfma_f32_16x16x32_bf16 v[36:39], v[110:113], v[106:109], v[36:39]
	v_mfma_f32_16x16x32_bf16 v[24:27], v[114:117], v[106:109], v[24:27]
	global_load_dwordx4 v[106:109], v[86:87], off offset:576
	global_load_dwordx4 v[110:113], v[88:89], off offset:576
	global_load_dwordx4 v[114:117], v[90:91], off offset:576
	s_waitcnt vmcnt(21)
	v_mfma_f32_16x16x32_bf16 v[36:39], v[122:125], v[118:121], v[36:39]
	v_mfma_f32_16x16x32_bf16 v[24:27], v[126:129], v[118:121], v[24:27]
	global_load_dwordx4 v[118:121], v[86:87], off offset:640
	global_load_dwordx4 v[122:125], v[88:89], off offset:640
	global_load_dwordx4 v[126:129], v[90:91], off offset:640
	s_waitcnt vmcnt(21)
	v_mfma_f32_16x16x32_bf16 v[36:39], v[134:137], v[130:133], v[36:39]
	v_mfma_f32_16x16x32_bf16 v[24:27], v[138:141], v[130:133], v[24:27]
	s_waitcnt vmcnt(18)
	v_mfma_f32_16x16x32_bf16 v[36:39], v[146:149], v[142:145], v[36:39]
	v_mfma_f32_16x16x32_bf16 v[24:27], v[150:153], v[142:145], v[24:27]
	s_waitcnt vmcnt(15)
	v_mfma_f32_16x16x32_bf16 v[36:39], v[158:161], v[154:157], v[36:39]
	v_mfma_f32_16x16x32_bf16 v[24:27], v[162:165], v[154:157], v[24:27]
	s_waitcnt vmcnt(12)
	v_mfma_f32_16x16x32_bf16 v[36:39], v[170:173], v[166:169], v[36:39]
	v_mfma_f32_16x16x32_bf16 v[24:27], v[174:177], v[166:169], v[24:27]
	s_waitcnt vmcnt(9)
	v_mfma_f32_16x16x32_bf16 v[36:39], v[182:185], v[178:181], v[36:39]
	v_mfma_f32_16x16x32_bf16 v[24:27], v[186:189], v[178:181], v[24:27]
	s_waitcnt vmcnt(6)
	v_mfma_f32_16x16x32_bf16 v[36:39], v[98:101], v[92:95], v[36:39]
	v_mfma_f32_16x16x32_bf16 v[24:27], v[102:105], v[92:95], v[24:27]
	s_waitcnt vmcnt(3)
	v_mfma_f32_16x16x32_bf16 v[36:39], v[110:113], v[106:109], v[36:39]
	v_mfma_f32_16x16x32_bf16 v[24:27], v[114:117], v[106:109], v[24:27]
	s_waitcnt vmcnt(0)
	v_mfma_f32_16x16x32_bf16 v[36:39], v[122:125], v[118:121], v[36:39]
	v_mfma_f32_16x16x32_bf16 v[24:27], v[126:129], v[118:121], v[24:27]
	s_nop 7
	s_nop 1
	ds_write_b128 v68, v[36:39]
	ds_write_b128 v68, v[24:27] offset:1024
	s_waitcnt lgkmcnt(0)
	s_waitcnt lgkmcnt(0)
	s_barrier
; __device__ __forceinline__ unsigned cvt_pk_bf16(float lo, float hi) { unsigned r; asm volatile("v_cvt_pk_bf16_f32 %0, %1, %2" : "=v"(r) : "v"(lo), "v"(hi)); return r; }
; template <int KSTEPS  >
; __device__ __forceinline__ void small_mma_ksplit(f32x4 (&acc)[2], const bf16_t* A, int lda, const bf16_t* Bt, int ldb, int n0, LAS unsigned char* lds, const SmallId& id) {
;     ...
;     acc[0] = (f32x4){0.f, 0.f, 0.f, 0.f}; acc[1] = acc[0];
; #pragma unroll
;     for (int w2 = 0; w2 < 8; ++w2) { acc[0] += red[((w2 * 8 + id.w) * 2 + 0) * 64 + lane]; acc[1] += red[((w2 * 8 + id.w) * 2 + 1) * 64 + lane]; }
;     asm volatile("s_waitcnt lgkmcnt(0)" ::: "memory"); __syncthreads();
; template <bool RES_F32, bool OUT_F32, int KSTEPS>
; __device__ __forceinline__ void small_res(const Params& p, LAS unsigned char* lds, const bf16_t* A, int lda, const bf16_t* Bt, int K, float* ssq_next, int G, int bx) {
;     ...
;         float s = 0.f;
; #pragma unroll
;         for (int nb = 0; nb < 2; ++nb) { const int col = n0 + 16 * nb + 4 * id.fq;
;             f32x4 r;
;             if (RES_F32) r = *(const f32x4*)(p.xs + (size_t)(id.row - MP) * DM + col);
;             else { const u32x2 w = *(const u32x2*)(XB + (size_t)id.row * DM + col); r = (f32x4){bf_lo(w.x), bf_hi(w.x), bf_lo(w.y), bf_hi(w.y)}; }
;             const f32x4 x = r + acc[nb];
;             if (OUT_F32) *(f32x4*)(p.out + (size_t)id.row * DM + col) = x;
;             else { u32x2 w; w.x = cvt_pk_bf16(x[0], x[1]); w.y = cvt_pk_bf16(x[2], x[3]); *(u32x2*)(XB + (size_t)id.row * DM + col) = w; }
;             s += (x[0] * x[0] + x[1] * x[1]) + (x[2] * x[2] + x[3] * x[3]); }
;         if (!OUT_F32) { s += __shfl_xor(s, 16); s += __shfl_xor(s, 32); if (id.fq == 0) atomicAdd(ssq_next + id.row, s); }
;     }
	ds_read_b128 v[92:95], v75
	ds_read_b128 v[98:101], v75 offset:1024
	ds_read_b128 v[102:105], v75 offset:16384
	ds_read_b128 v[106:109], v75 offset:17408
	ds_read_b128 v[110:113], v75 offset:32768
	ds_read_b128 v[114:117], v75 offset:33792
	ds_read_b128 v[118:121], v75 offset:49152
	ds_read_b128 v[122:125], v75 offset:50176
	ds_read_b128 v[126:129], v76
	ds_read_b128 v[130:133], v77
	ds_read_b128 v[134:137], v78
	ds_read_b128 v[138:141], v79
	ds_read_b128 v[142:145], v80
	ds_read_b128 v[146:149], v81
	ds_read_b128 v[150:153], v82
	ds_read_b128 v[0:3], v83
	s_waitcnt lgkmcnt(0)
	v_pk_add_f32 v[4:5], v[94:95], 0 op_sel_hi:[1,0]
	v_pk_add_f32 v[6:7], v[92:93], 0 op_sel_hi:[1,0]
	v_pk_add_f32 v[8:9], v[100:101], 0 op_sel_hi:[1,0]
	v_pk_add_f32 v[10:11], v[98:99], 0 op_sel_hi:[1,0]
	v_pk_add_f32 v[4:5], v[4:5], v[104:105]
	v_pk_add_f32 v[6:7], v[6:7], v[102:103]
	v_pk_add_f32 v[8:9], v[8:9], v[108:109]
	v_pk_add_f32 v[10:11], v[10:11], v[106:107]
	v_pk_add_f32 v[4:5], v[4:5], v[112:113]
	v_pk_add_f32 v[6:7], v[6:7], v[110:111]
	v_pk_add_f32 v[8:9], v[8:9], v[116:117]
	v_pk_add_f32 v[10:11], v[10:11], v[114:115]
	v_pk_add_f32 v[4:5], v[4:5], v[120:121]
	v_pk_add_f32 v[6:7], v[6:7], v[118:119]
	v_pk_add_f32 v[8:9], v[8:9], v[124:125]
	v_pk_add_f32 v[10:11], v[10:11], v[122:123]
	v_pk_add_f32 v[4:5], v[4:5], v[128:129]
	v_pk_add_f32 v[6:7], v[6:7], v[126:127]
	v_pk_add_f32 v[8:9], v[8:9], v[132:133]
	v_pk_add_f32 v[10:11], v[10:11], v[130:131]
	v_pk_add_f32 v[4:5], v[4:5], v[136:137]
	v_pk_add_f32 v[6:7], v[6:7], v[134:135]
	v_pk_add_f32 v[8:9], v[8:9], v[140:141]
	v_pk_add_f32 v[10:11], v[10:11], v[138:139]
	v_pk_add_f32 v[4:5], v[4:5], v[144:145]
	v_pk_add_f32 v[6:7], v[6:7], v[142:143]
	v_pk_add_f32 v[8:9], v[8:9], v[148:149]
	v_pk_add_f32 v[10:11], v[10:11], v[146:147]
	v_pk_add_f32 v[4:5], v[4:5], v[152:153]
	v_pk_add_f32 v[6:7], v[6:7], v[150:151]
	s_waitcnt lgkmcnt(0)
	s_waitcnt lgkmcnt(0)
	s_barrier
	s_mul_i32 exec_lo, s32, -1
	s_mov_b32 exec_hi, exec_lo
	v_pk_add_f32 v[2:3], v[8:9], v[2:3]
	v_lshl_or_b32 v8, s7, 5, v84
	v_ashrrev_i32_e32 v9, 31, v8
	v_lshl_add_u64 v[8:9], v[8:9], 1, v[64:65]
	v_pk_add_f32 v[0:1], v[10:11], v[0:1]
	v_mov_b64_e32 v[10:11], v[250:251]
	s_waitcnt vmcnt(0) lgkmcnt(0)
	v_lshlrev_b32_e32 v12, 16, v10
	v_and_b32_e32 v13, 0xffff0000, v10
	v_lshlrev_b32_e32 v10, 16, v11
	v_and_b32_e32 v11, 0xffff0000, v11
	v_pk_add_f32 v[4:5], v[4:5], v[10:11]
	v_pk_add_f32 v[6:7], v[6:7], v[12:13]
	s_nop 0
	v_cvt_pk_bf16_f32 v10, v6, v7
	v_cvt_pk_bf16_f32 v11, v4, v5
	v_mul_f32_e32 v7, v7, v7
	v_mul_f32_e32 v5, v5, v5
	v_fmac_f32_e32 v7, v6, v6
	v_fmac_f32_e32 v5, v4, v4
	global_store_dwordx2 v[8:9], v[10:11], off
	v_add_f32_e32 v10, v7, v5
	s_waitcnt vmcnt(0) lgkmcnt(0)
	v_lshlrev_b32_e32 v6, 16, v234
	v_and_b32_e32 v7, 0xffff0000, v234
	v_lshlrev_b32_e32 v4, 16, v235
	v_and_b32_e32 v5, 0xffff0000, v235
	v_pk_add_f32 v[0:1], v[0:1], v[6:7]
	v_pk_add_f32 v[2:3], v[2:3], v[4:5]
	v_cvt_pk_bf16_f32 v4, v0, v1
	v_mul_f32_e32 v1, v1, v1
	v_fmac_f32_e32 v1, v0, v0
	v_mul_f32_e32 v0, v3, v3
	v_cvt_pk_bf16_f32 v5, v2, v3
	v_fmac_f32_e32 v0, v2, v2
	v_and_b32_e32 v2, 64, v225
	v_add_f32_e32 v0, v1, v0
	v_xor_b32_e32 v1, 16, v225
	v_add_u32_e32 v2, 64, v2
	v_cmp_lt_i32_e64 s[0:1], v1, v2
	v_add_f32_e32 v0, v10, v0
	global_store_dwordx2 v[8:9], v[4:5], off offset:32
	v_cndmask_b32_e64 v1, v225, v1, s[0:1]
	v_lshlrev_b32_e32 v1, 2, v1
	ds_bpermute_b32 v1, v1, v0
	s_waitcnt lgkmcnt(0)
	v_add_f32_e32 v0, v0, v1
	v_xor_b32_e32 v1, 32, v225
	v_cmp_lt_i32_e64 s[0:1], v1, v2
	s_nop 1
	v_cndmask_b32_e64 v1, v225, v1, s[0:1]
	v_lshlrev_b32_e32 v1, 2, v1
	ds_bpermute_b32 v1, v1, v0
	s_and_saveexec_b64 s[0:1], vcc
	s_cbranch_execz .LBB0_1253
	s_waitcnt lgkmcnt(0)
	v_add_f32_e32 v0, v0, v1
	global_atomic_add_f32 v[66:67], v0, off
	s_branch .LBB0_1253
